# removed 5 per-tile vmcnt(0) waits in GEMM tile pre-headers (P5,P7,P15,P16,P17) on top of P6 deferred-store epilogue
# speedup vs baseline: 1.0022x; 1.0018x over previous
.LBB0_899:
	s_ashr_i32 s31, s30, 31
	v_cmp_lt_i64_e32 vcc, s[36:37], v[188:189]
	s_lshl_b64 s[36:37], s[30:31], 19
	s_add_u32 s36, s12, s36
	s_addc_u32 s37, s13, s37
	s_and_b64 s[38:39], vcc, exec
	s_cselect_b32 s31, s37, s55
	s_cselect_b32 s51, s36, s54
	s_ashr_i32 s27, s26, 31
	s_lshl_b64 s[38:39], s[26:27], 19
	s_add_u32 s38, s1, s38
	s_addc_u32 s39, s2, s39
	s_and_b64 s[58:59], vcc, exec
	s_cselect_b32 s27, s39, s57
	s_cselect_b32 s53, s38, s56
	s_add_u32 s54, s54, 0x40080
	s_addc_u32 s55, s55, 0
	s_add_u32 s60, s56, 0x100
	v_mov_b32_e32 v0, 0
	s_addc_u32 s61, s57, 0
	s_mov_b32 s62, -2
	s_waitcnt lgkmcnt(0)
	v_mov_b32_e32 v1, v0
	v_mov_b32_e32 v2, v0
	v_mov_b32_e32 v3, v0
	v_mov_b32_e32 v4, v0
	v_mov_b32_e32 v5, v0
	v_mov_b32_e32 v6, v0
	v_mov_b32_e32 v7, v0
	v_mov_b32_e32 v16, v0
	v_mov_b32_e32 v17, v0
	v_mov_b32_e32 v18, v0
	v_mov_b32_e32 v19, v0
	v_mov_b32_e32 v20, v0
	v_mov_b32_e32 v21, v0
	v_mov_b32_e32 v22, v0
	v_mov_b32_e32 v23, v0
	v_mov_b32_e32 v32, v0
	v_mov_b32_e32 v33, v0
	v_mov_b32_e32 v34, v0
	v_mov_b32_e32 v35, v0
	v_mov_b32_e32 v36, v0
	v_mov_b32_e32 v37, v0
	v_mov_b32_e32 v38, v0
	v_mov_b32_e32 v39, v0
	v_mov_b32_e32 v48, v0
	v_mov_b32_e32 v49, v0
	v_mov_b32_e32 v50, v0
	v_mov_b32_e32 v51, v0
	v_mov_b32_e32 v52, v0
	v_mov_b32_e32 v53, v0
	v_mov_b32_e32 v54, v0
	v_mov_b32_e32 v55, v0
	v_mov_b32_e32 v8, v0
	v_mov_b32_e32 v9, v0
	v_mov_b32_e32 v10, v0
	v_mov_b32_e32 v11, v0
	v_mov_b32_e32 v12, v0
	v_mov_b32_e32 v13, v0
	v_mov_b32_e32 v14, v0
	v_mov_b32_e32 v15, v0
	v_mov_b32_e32 v24, v0
	v_mov_b32_e32 v25, v0
	v_mov_b32_e32 v26, v0
	v_mov_b32_e32 v27, v0
	v_mov_b32_e32 v28, v0
	v_mov_b32_e32 v29, v0
	v_mov_b32_e32 v30, v0
	v_mov_b32_e32 v31, v0
	v_mov_b32_e32 v40, v0
	v_mov_b32_e32 v41, v0
	v_mov_b32_e32 v42, v0
	v_mov_b32_e32 v43, v0
	v_mov_b32_e32 v44, v0
	v_mov_b32_e32 v45, v0
	v_mov_b32_e32 v46, v0
	v_mov_b32_e32 v47, v0
	v_mov_b32_e32 v56, v0
	v_mov_b32_e32 v57, v0
	v_mov_b32_e32 v58, v0
	v_mov_b32_e32 v59, v0
	v_mov_b32_e32 v60, v0
	v_mov_b32_e32 v61, v0
	v_mov_b32_e32 v62, v0
	v_mov_b32_e32 v63, v0
	v_mov_b32_e32 v64, v0
	v_mov_b32_e32 v65, v0
	v_mov_b32_e32 v66, v0
	v_mov_b32_e32 v67, v0
	v_mov_b32_e32 v68, v0
	v_mov_b32_e32 v69, v0
	v_mov_b32_e32 v70, v0
	v_mov_b32_e32 v71, v0
	v_mov_b32_e32 v80, v0
	v_mov_b32_e32 v81, v0
	v_mov_b32_e32 v82, v0
	v_mov_b32_e32 v83, v0
	v_mov_b32_e32 v84, v0
	v_mov_b32_e32 v85, v0
	v_mov_b32_e32 v86, v0
	v_mov_b32_e32 v87, v0
	v_mov_b32_e32 v96, v0
	v_mov_b32_e32 v97, v0
	v_mov_b32_e32 v98, v0
	v_mov_b32_e32 v99, v0
	v_mov_b32_e32 v100, v0
	v_mov_b32_e32 v101, v0
	v_mov_b32_e32 v102, v0
	v_mov_b32_e32 v103, v0
	v_mov_b32_e32 v112, v0
	v_mov_b32_e32 v113, v0
	v_mov_b32_e32 v114, v0
	v_mov_b32_e32 v115, v0
	v_mov_b32_e32 v116, v0
	v_mov_b32_e32 v117, v0
	v_mov_b32_e32 v118, v0
	v_mov_b32_e32 v119, v0
	v_mov_b32_e32 v72, v0
	v_mov_b32_e32 v73, v0
	v_mov_b32_e32 v74, v0
	v_mov_b32_e32 v75, v0
	v_mov_b32_e32 v76, v0
	v_mov_b32_e32 v77, v0
	v_mov_b32_e32 v78, v0
	v_mov_b32_e32 v79, v0
	v_mov_b32_e32 v88, v0
	v_mov_b32_e32 v89, v0
	v_mov_b32_e32 v90, v0
	v_mov_b32_e32 v91, v0
	v_mov_b32_e32 v92, v0
	v_mov_b32_e32 v93, v0
	v_mov_b32_e32 v94, v0
	v_mov_b32_e32 v95, v0
	v_mov_b32_e32 v104, v0
	v_mov_b32_e32 v105, v0
	v_mov_b32_e32 v106, v0
	v_mov_b32_e32 v107, v0
	v_mov_b32_e32 v108, v0
	v_mov_b32_e32 v109, v0
	v_mov_b32_e32 v110, v0
	v_mov_b32_e32 v111, v0
	v_mov_b32_e32 v120, v0
	v_mov_b32_e32 v121, v0
	v_mov_b32_e32 v122, v0
	v_mov_b32_e32 v123, v0
	v_mov_b32_e32 v124, v0
	v_mov_b32_e32 v125, v0
	v_mov_b32_e32 v126, v0
	v_mov_b32_e32 v127, v0

.LBB0_1061:
	s_ashr_i32 s27, s26, 31
	v_cmp_lt_i64_e32 vcc, s[28:29], v[164:165]
	s_lshl_b64 s[28:29], s[26:27], 21
	s_add_u32 s28, s1, s28
	s_addc_u32 s29, s2, s29
	s_and_b64 s[30:31], vcc, exec
	s_cselect_b32 s27, s29, s51
	s_cselect_b32 s37, s28, s50
	s_ashr_i32 s25, s24, 31
	s_lshl_b64 s[30:31], s[24:25], 21
	s_add_u32 s30, s20, s30
	s_addc_u32 s31, s21, s31
	s_and_b64 s[54:55], vcc, exec
	s_cselect_b32 s25, s31, s53
	s_cselect_b32 s57, s30, s52
	s_add_u32 s50, s50, 0x100080
	s_addc_u32 s51, s51, 0
	s_add_u32 s58, s52, 0x100
	v_mov_b32_e32 v0, 0
	s_addc_u32 s59, s53, 0
	s_mov_b32 s60, -2
	s_waitcnt lgkmcnt(0)
	v_mov_b32_e32 v1, v0
	v_mov_b32_e32 v2, v0
	v_mov_b32_e32 v3, v0
	v_mov_b32_e32 v4, v0
	v_mov_b32_e32 v5, v0
	v_mov_b32_e32 v6, v0
	v_mov_b32_e32 v7, v0
	v_mov_b32_e32 v16, v0
	v_mov_b32_e32 v17, v0
	v_mov_b32_e32 v18, v0
	v_mov_b32_e32 v19, v0
	v_mov_b32_e32 v20, v0
	v_mov_b32_e32 v21, v0
	v_mov_b32_e32 v22, v0
	v_mov_b32_e32 v23, v0
	v_mov_b32_e32 v32, v0
	v_mov_b32_e32 v33, v0
	v_mov_b32_e32 v34, v0
	v_mov_b32_e32 v35, v0
	v_mov_b32_e32 v36, v0
	v_mov_b32_e32 v37, v0
	v_mov_b32_e32 v38, v0
	v_mov_b32_e32 v39, v0
	v_mov_b32_e32 v48, v0
	v_mov_b32_e32 v49, v0
	v_mov_b32_e32 v50, v0
	v_mov_b32_e32 v51, v0
	v_mov_b32_e32 v52, v0
	v_mov_b32_e32 v53, v0
	v_mov_b32_e32 v54, v0
	v_mov_b32_e32 v55, v0
	v_mov_b32_e32 v8, v0
	v_mov_b32_e32 v9, v0
	v_mov_b32_e32 v10, v0
	v_mov_b32_e32 v11, v0
	v_mov_b32_e32 v12, v0
	v_mov_b32_e32 v13, v0
	v_mov_b32_e32 v14, v0
	v_mov_b32_e32 v15, v0
	v_mov_b32_e32 v24, v0
	v_mov_b32_e32 v25, v0
	v_mov_b32_e32 v26, v0
	v_mov_b32_e32 v27, v0
	v_mov_b32_e32 v28, v0
	v_mov_b32_e32 v29, v0
	v_mov_b32_e32 v30, v0
	v_mov_b32_e32 v31, v0
	v_mov_b32_e32 v40, v0
	v_mov_b32_e32 v41, v0
	v_mov_b32_e32 v42, v0
	v_mov_b32_e32 v43, v0
	v_mov_b32_e32 v44, v0
	v_mov_b32_e32 v45, v0
	v_mov_b32_e32 v46, v0
	v_mov_b32_e32 v47, v0
	v_mov_b32_e32 v56, v0
	v_mov_b32_e32 v57, v0
	v_mov_b32_e32 v58, v0
	v_mov_b32_e32 v59, v0
	v_mov_b32_e32 v60, v0
	v_mov_b32_e32 v61, v0
	v_mov_b32_e32 v62, v0
	v_mov_b32_e32 v63, v0
	v_mov_b32_e32 v64, v0
	v_mov_b32_e32 v65, v0
	v_mov_b32_e32 v66, v0
	v_mov_b32_e32 v67, v0
	v_mov_b32_e32 v68, v0
	v_mov_b32_e32 v69, v0
	v_mov_b32_e32 v70, v0
	v_mov_b32_e32 v71, v0
	v_mov_b32_e32 v80, v0
	v_mov_b32_e32 v81, v0
	v_mov_b32_e32 v82, v0
	v_mov_b32_e32 v83, v0
	v_mov_b32_e32 v84, v0
	v_mov_b32_e32 v85, v0
	v_mov_b32_e32 v86, v0
	v_mov_b32_e32 v87, v0
	v_mov_b32_e32 v96, v0
	v_mov_b32_e32 v97, v0
	v_mov_b32_e32 v98, v0
	v_mov_b32_e32 v99, v0
	v_mov_b32_e32 v100, v0
	v_mov_b32_e32 v101, v0
	v_mov_b32_e32 v102, v0
	v_mov_b32_e32 v103, v0
	v_mov_b32_e32 v112, v0
	v_mov_b32_e32 v113, v0
	v_mov_b32_e32 v114, v0
	v_mov_b32_e32 v115, v0
	v_mov_b32_e32 v116, v0
	v_mov_b32_e32 v117, v0
	v_mov_b32_e32 v118, v0
	v_mov_b32_e32 v119, v0
	v_mov_b32_e32 v72, v0
	v_mov_b32_e32 v73, v0
	v_mov_b32_e32 v74, v0
	v_mov_b32_e32 v75, v0
	v_mov_b32_e32 v76, v0
	v_mov_b32_e32 v77, v0
	v_mov_b32_e32 v78, v0
	v_mov_b32_e32 v79, v0
	v_mov_b32_e32 v88, v0
	v_mov_b32_e32 v89, v0
	v_mov_b32_e32 v90, v0
	v_mov_b32_e32 v91, v0
	v_mov_b32_e32 v92, v0
	v_mov_b32_e32 v93, v0
	v_mov_b32_e32 v94, v0
	v_mov_b32_e32 v95, v0
	v_mov_b32_e32 v104, v0
	v_mov_b32_e32 v105, v0
	v_mov_b32_e32 v106, v0
	v_mov_b32_e32 v107, v0
	v_mov_b32_e32 v108, v0
	v_mov_b32_e32 v109, v0
	v_mov_b32_e32 v110, v0
	v_mov_b32_e32 v111, v0
	v_mov_b32_e32 v120, v0
	v_mov_b32_e32 v121, v0
	v_mov_b32_e32 v122, v0
	v_mov_b32_e32 v123, v0
	v_mov_b32_e32 v124, v0
	v_mov_b32_e32 v125, v0
	v_mov_b32_e32 v126, v0
	v_mov_b32_e32 v127, v0

.LBB0_1893:
	s_ashr_i32 s29, s28, 31
	v_cmp_lt_i64_e32 vcc, s[30:31], v[164:165]
	s_lshl_b64 s[30:31], s[28:29], 19
	s_add_u32 s30, s12, s30
	s_addc_u32 s31, s13, s31
	s_and_b64 s[34:35], vcc, exec
	s_cselect_b32 s29, s31, s41
	s_cselect_b32 s37, s30, s40
	s_ashr_i32 s27, s26, 31
	s_lshl_b64 s[34:35], s[26:27], 19
	s_add_u32 s34, s1, s34
	s_addc_u32 s35, s2, s35
	s_and_b64 s[44:45], vcc, exec
	s_cselect_b32 s27, s35, s43
	s_cselect_b32 s54, s34, s42
	s_add_u32 s40, s40, 0x40080
	s_addc_u32 s41, s41, 0
	s_add_u32 s55, s42, 0x100
	v_mov_b32_e32 v0, 0
	s_addc_u32 s56, s43, 0
	s_mov_b32 s57, -2
	s_waitcnt lgkmcnt(0)
	v_mov_b32_e32 v1, v0
	v_mov_b32_e32 v2, v0
	v_mov_b32_e32 v3, v0
	v_mov_b32_e32 v4, v0
	v_mov_b32_e32 v5, v0
	v_mov_b32_e32 v6, v0
	v_mov_b32_e32 v7, v0
	v_mov_b32_e32 v16, v0
	v_mov_b32_e32 v17, v0
	v_mov_b32_e32 v18, v0
	v_mov_b32_e32 v19, v0
	v_mov_b32_e32 v20, v0
	v_mov_b32_e32 v21, v0
	v_mov_b32_e32 v22, v0
	v_mov_b32_e32 v23, v0
	v_mov_b32_e32 v32, v0
	v_mov_b32_e32 v33, v0
	v_mov_b32_e32 v34, v0
	v_mov_b32_e32 v35, v0
	v_mov_b32_e32 v36, v0
	v_mov_b32_e32 v37, v0
	v_mov_b32_e32 v38, v0
	v_mov_b32_e32 v39, v0
	v_mov_b32_e32 v48, v0
	v_mov_b32_e32 v49, v0
	v_mov_b32_e32 v50, v0
	v_mov_b32_e32 v51, v0
	v_mov_b32_e32 v52, v0
	v_mov_b32_e32 v53, v0
	v_mov_b32_e32 v54, v0
	v_mov_b32_e32 v55, v0
	v_mov_b32_e32 v8, v0
	v_mov_b32_e32 v9, v0
	v_mov_b32_e32 v10, v0
	v_mov_b32_e32 v11, v0
	v_mov_b32_e32 v12, v0
	v_mov_b32_e32 v13, v0
	v_mov_b32_e32 v14, v0
	v_mov_b32_e32 v15, v0
	v_mov_b32_e32 v24, v0
	v_mov_b32_e32 v25, v0
	v_mov_b32_e32 v26, v0
	v_mov_b32_e32 v27, v0
	v_mov_b32_e32 v28, v0
	v_mov_b32_e32 v29, v0
	v_mov_b32_e32 v30, v0
	v_mov_b32_e32 v31, v0
	v_mov_b32_e32 v40, v0
	v_mov_b32_e32 v41, v0
	v_mov_b32_e32 v42, v0
	v_mov_b32_e32 v43, v0
	v_mov_b32_e32 v44, v0
	v_mov_b32_e32 v45, v0
	v_mov_b32_e32 v46, v0
	v_mov_b32_e32 v47, v0
	v_mov_b32_e32 v56, v0
	v_mov_b32_e32 v57, v0
	v_mov_b32_e32 v58, v0
	v_mov_b32_e32 v59, v0
	v_mov_b32_e32 v60, v0
	v_mov_b32_e32 v61, v0
	v_mov_b32_e32 v62, v0
	v_mov_b32_e32 v63, v0
	v_mov_b32_e32 v64, v0
	v_mov_b32_e32 v65, v0
	v_mov_b32_e32 v66, v0
	v_mov_b32_e32 v67, v0
	v_mov_b32_e32 v68, v0
	v_mov_b32_e32 v69, v0
	v_mov_b32_e32 v70, v0
	v_mov_b32_e32 v71, v0
	v_mov_b32_e32 v80, v0
	v_mov_b32_e32 v81, v0
	v_mov_b32_e32 v82, v0
	v_mov_b32_e32 v83, v0
	v_mov_b32_e32 v84, v0
	v_mov_b32_e32 v85, v0
	v_mov_b32_e32 v86, v0
	v_mov_b32_e32 v87, v0
	v_mov_b32_e32 v96, v0
	v_mov_b32_e32 v97, v0
	v_mov_b32_e32 v98, v0
	v_mov_b32_e32 v99, v0
	v_mov_b32_e32 v100, v0
	v_mov_b32_e32 v101, v0
	v_mov_b32_e32 v102, v0
	v_mov_b32_e32 v103, v0
	v_mov_b32_e32 v112, v0
	v_mov_b32_e32 v113, v0
	v_mov_b32_e32 v114, v0
	v_mov_b32_e32 v115, v0
	v_mov_b32_e32 v116, v0
	v_mov_b32_e32 v117, v0
	v_mov_b32_e32 v118, v0
	v_mov_b32_e32 v119, v0
	v_mov_b32_e32 v72, v0
	v_mov_b32_e32 v73, v0
	v_mov_b32_e32 v74, v0
	v_mov_b32_e32 v75, v0
	v_mov_b32_e32 v76, v0
	v_mov_b32_e32 v77, v0
	v_mov_b32_e32 v78, v0
	v_mov_b32_e32 v79, v0
	v_mov_b32_e32 v88, v0
	v_mov_b32_e32 v89, v0
	v_mov_b32_e32 v90, v0
	v_mov_b32_e32 v91, v0
	v_mov_b32_e32 v92, v0
	v_mov_b32_e32 v93, v0
	v_mov_b32_e32 v94, v0
	v_mov_b32_e32 v95, v0
	v_mov_b32_e32 v104, v0
	v_mov_b32_e32 v105, v0
	v_mov_b32_e32 v106, v0
	v_mov_b32_e32 v107, v0
	v_mov_b32_e32 v108, v0
	v_mov_b32_e32 v109, v0
	v_mov_b32_e32 v110, v0
	v_mov_b32_e32 v111, v0
	v_mov_b32_e32 v120, v0
	v_mov_b32_e32 v121, v0
	v_mov_b32_e32 v122, v0
	v_mov_b32_e32 v123, v0
	v_mov_b32_e32 v124, v0
	v_mov_b32_e32 v125, v0
	v_mov_b32_e32 v126, v0
	v_mov_b32_e32 v127, v0

.LBB0_1980:
	s_ashr_i32 s37, s36, 31
	v_cmp_lt_i64_e32 vcc, s[38:39], v[140:141]
	s_lshl_b64 s[38:39], s[36:37], 19
	s_add_u32 s38, s2, s38
	s_addc_u32 s39, s3, s39
	s_and_b64 s[40:41], vcc, exec
	s_cselect_b32 s9, s39, s11
	s_cselect_b32 s37, s38, s10
	s_ashr_i32 s35, s34, 31
	s_lshl_b64 s[40:41], s[34:35], 19
	s_add_u32 s40, s20, s40
	s_addc_u32 s41, s21, s41
	s_and_b64 s[44:45], vcc, exec
	s_cselect_b32 s35, s41, s43
	s_cselect_b32 s63, s40, s42
	s_add_u32 s10, s10, 0x40080
	s_addc_u32 s11, s11, 0
	s_add_u32 s64, s42, 0x100
	v_mov_b32_e32 v0, 0
	s_addc_u32 s65, s43, 0
	s_mov_b32 s66, -2
	v_mov_b32_e32 v1, v0
	v_mov_b32_e32 v2, v0
	v_mov_b32_e32 v3, v0
	v_mov_b32_e32 v4, v0
	v_mov_b32_e32 v5, v0
	v_mov_b32_e32 v6, v0
	v_mov_b32_e32 v7, v0
	v_mov_b32_e32 v16, v0
	v_mov_b32_e32 v17, v0
	v_mov_b32_e32 v18, v0
	v_mov_b32_e32 v19, v0
	v_mov_b32_e32 v20, v0
	v_mov_b32_e32 v21, v0
	v_mov_b32_e32 v22, v0
	v_mov_b32_e32 v23, v0
	v_mov_b32_e32 v32, v0
	v_mov_b32_e32 v33, v0
	v_mov_b32_e32 v34, v0
	v_mov_b32_e32 v35, v0
	v_mov_b32_e32 v36, v0
	v_mov_b32_e32 v37, v0
	v_mov_b32_e32 v38, v0
	v_mov_b32_e32 v39, v0
	v_mov_b32_e32 v48, v0
	v_mov_b32_e32 v49, v0
	v_mov_b32_e32 v50, v0
	v_mov_b32_e32 v51, v0
	v_mov_b32_e32 v52, v0
	v_mov_b32_e32 v53, v0
	v_mov_b32_e32 v54, v0
	v_mov_b32_e32 v55, v0
	v_mov_b32_e32 v8, v0
	v_mov_b32_e32 v9, v0
	v_mov_b32_e32 v10, v0
	v_mov_b32_e32 v11, v0
	v_mov_b32_e32 v12, v0
	v_mov_b32_e32 v13, v0
	v_mov_b32_e32 v14, v0
	v_mov_b32_e32 v15, v0
	v_mov_b32_e32 v24, v0
	v_mov_b32_e32 v25, v0
	v_mov_b32_e32 v26, v0
	v_mov_b32_e32 v27, v0
	v_mov_b32_e32 v28, v0
	v_mov_b32_e32 v29, v0
	v_mov_b32_e32 v30, v0
	v_mov_b32_e32 v31, v0
	v_mov_b32_e32 v40, v0
	v_mov_b32_e32 v41, v0
	v_mov_b32_e32 v42, v0
	v_mov_b32_e32 v43, v0
	v_mov_b32_e32 v44, v0
	v_mov_b32_e32 v45, v0
	v_mov_b32_e32 v46, v0
	v_mov_b32_e32 v47, v0
	v_mov_b32_e32 v56, v0
	v_mov_b32_e32 v57, v0
	v_mov_b32_e32 v58, v0
	v_mov_b32_e32 v59, v0
	v_mov_b32_e32 v60, v0
	v_mov_b32_e32 v61, v0
	v_mov_b32_e32 v62, v0
	v_mov_b32_e32 v63, v0
	v_mov_b32_e32 v64, v0
	v_mov_b32_e32 v65, v0
	v_mov_b32_e32 v66, v0
	v_mov_b32_e32 v67, v0
	v_mov_b32_e32 v68, v0
	v_mov_b32_e32 v69, v0
	v_mov_b32_e32 v70, v0
	v_mov_b32_e32 v71, v0
	v_mov_b32_e32 v80, v0
	v_mov_b32_e32 v81, v0
	v_mov_b32_e32 v82, v0
	v_mov_b32_e32 v83, v0
	v_mov_b32_e32 v84, v0
	v_mov_b32_e32 v85, v0
	v_mov_b32_e32 v86, v0
	v_mov_b32_e32 v87, v0
	v_mov_b32_e32 v96, v0
	v_mov_b32_e32 v97, v0
	v_mov_b32_e32 v98, v0
	v_mov_b32_e32 v99, v0
	v_mov_b32_e32 v100, v0
	v_mov_b32_e32 v101, v0
	v_mov_b32_e32 v102, v0
	v_mov_b32_e32 v103, v0
	v_mov_b32_e32 v112, v0
	v_mov_b32_e32 v113, v0
	v_mov_b32_e32 v114, v0
	v_mov_b32_e32 v115, v0
	v_mov_b32_e32 v116, v0
	v_mov_b32_e32 v117, v0
	v_mov_b32_e32 v118, v0
	v_mov_b32_e32 v119, v0
	v_mov_b32_e32 v72, v0
	v_mov_b32_e32 v73, v0
	v_mov_b32_e32 v74, v0
	v_mov_b32_e32 v75, v0
	v_mov_b32_e32 v76, v0
	v_mov_b32_e32 v77, v0
	v_mov_b32_e32 v78, v0
	v_mov_b32_e32 v79, v0
	v_mov_b32_e32 v88, v0
	v_mov_b32_e32 v89, v0
	v_mov_b32_e32 v90, v0
	v_mov_b32_e32 v91, v0
	v_mov_b32_e32 v92, v0
	v_mov_b32_e32 v93, v0
	v_mov_b32_e32 v94, v0
	v_mov_b32_e32 v95, v0
	v_mov_b32_e32 v104, v0
	v_mov_b32_e32 v105, v0
	v_mov_b32_e32 v106, v0
	v_mov_b32_e32 v107, v0
	v_mov_b32_e32 v108, v0
	v_mov_b32_e32 v109, v0
	v_mov_b32_e32 v110, v0
	v_mov_b32_e32 v111, v0
	v_mov_b32_e32 v120, v0
	v_mov_b32_e32 v121, v0
	v_mov_b32_e32 v122, v0
	v_mov_b32_e32 v123, v0
	v_mov_b32_e32 v124, v0
	v_mov_b32_e32 v125, v0
	v_mov_b32_e32 v126, v0
	v_mov_b32_e32 v127, v0

.LBB0_2055:
	s_ashr_i32 s19, s18, 31
	v_cmp_lt_i64_e32 vcc, s[24:25], v[164:165]
	s_lshl_b64 s[24:25], s[18:19], 21
	s_add_u32 s24, s1, s24
	s_addc_u32 s25, s2, s25
	s_and_b64 s[26:27], vcc, exec
	s_cselect_b32 s19, s25, s35
	s_cselect_b32 s29, s24, s34
	s_ashr_i32 s17, s16, 31
	s_lshl_b64 s[26:27], s[16:17], 21
	s_add_u32 s26, s3, s26
	s_addc_u32 s27, s20, s27
	s_and_b64 s[38:39], vcc, exec
	s_cselect_b32 s17, s27, s37
	s_cselect_b32 s50, s26, s36
	s_add_u32 s34, s34, 0x100080
	s_addc_u32 s35, s35, 0
	s_add_u32 s51, s36, 0x100
	v_mov_b32_e32 v0, 0
	s_addc_u32 s52, s37, 0
	s_mov_b32 s53, -2
	s_waitcnt lgkmcnt(0)
	v_mov_b32_e32 v1, v0
	v_mov_b32_e32 v2, v0
	v_mov_b32_e32 v3, v0
	v_mov_b32_e32 v4, v0
	v_mov_b32_e32 v5, v0
	v_mov_b32_e32 v6, v0
	v_mov_b32_e32 v7, v0
	v_mov_b32_e32 v16, v0
	v_mov_b32_e32 v17, v0
	v_mov_b32_e32 v18, v0
	v_mov_b32_e32 v19, v0
	v_mov_b32_e32 v20, v0
	v_mov_b32_e32 v21, v0
	v_mov_b32_e32 v22, v0
	v_mov_b32_e32 v23, v0
	v_mov_b32_e32 v32, v0
	v_mov_b32_e32 v33, v0
	v_mov_b32_e32 v34, v0
	v_mov_b32_e32 v35, v0
	v_mov_b32_e32 v36, v0
	v_mov_b32_e32 v37, v0
	v_mov_b32_e32 v38, v0
	v_mov_b32_e32 v39, v0
	v_mov_b32_e32 v48, v0
	v_mov_b32_e32 v49, v0
	v_mov_b32_e32 v50, v0
	v_mov_b32_e32 v51, v0
	v_mov_b32_e32 v52, v0
	v_mov_b32_e32 v53, v0
	v_mov_b32_e32 v54, v0
	v_mov_b32_e32 v55, v0
	v_mov_b32_e32 v8, v0
	v_mov_b32_e32 v9, v0
	v_mov_b32_e32 v10, v0
	v_mov_b32_e32 v11, v0
	v_mov_b32_e32 v12, v0
	v_mov_b32_e32 v13, v0
	v_mov_b32_e32 v14, v0
	v_mov_b32_e32 v15, v0
	v_mov_b32_e32 v24, v0
	v_mov_b32_e32 v25, v0
	v_mov_b32_e32 v26, v0
	v_mov_b32_e32 v27, v0
	v_mov_b32_e32 v28, v0
	v_mov_b32_e32 v29, v0
	v_mov_b32_e32 v30, v0
	v_mov_b32_e32 v31, v0
	v_mov_b32_e32 v40, v0
	v_mov_b32_e32 v41, v0
	v_mov_b32_e32 v42, v0
	v_mov_b32_e32 v43, v0
	v_mov_b32_e32 v44, v0
	v_mov_b32_e32 v45, v0
	v_mov_b32_e32 v46, v0
	v_mov_b32_e32 v47, v0
	v_mov_b32_e32 v56, v0
	v_mov_b32_e32 v57, v0
	v_mov_b32_e32 v58, v0
	v_mov_b32_e32 v59, v0
	v_mov_b32_e32 v60, v0
	v_mov_b32_e32 v61, v0
	v_mov_b32_e32 v62, v0
	v_mov_b32_e32 v63, v0
	v_mov_b32_e32 v64, v0
	v_mov_b32_e32 v65, v0
	v_mov_b32_e32 v66, v0
	v_mov_b32_e32 v67, v0
	v_mov_b32_e32 v68, v0
	v_mov_b32_e32 v69, v0
	v_mov_b32_e32 v70, v0
	v_mov_b32_e32 v71, v0
	v_mov_b32_e32 v80, v0
	v_mov_b32_e32 v81, v0
	v_mov_b32_e32 v82, v0
	v_mov_b32_e32 v83, v0
	v_mov_b32_e32 v84, v0
	v_mov_b32_e32 v85, v0
	v_mov_b32_e32 v86, v0
	v_mov_b32_e32 v87, v0
	v_mov_b32_e32 v96, v0
	v_mov_b32_e32 v97, v0
	v_mov_b32_e32 v98, v0
	v_mov_b32_e32 v99, v0
	v_mov_b32_e32 v100, v0
	v_mov_b32_e32 v101, v0
	v_mov_b32_e32 v102, v0
	v_mov_b32_e32 v103, v0
	v_mov_b32_e32 v112, v0
	v_mov_b32_e32 v113, v0
	v_mov_b32_e32 v114, v0
	v_mov_b32_e32 v115, v0
	v_mov_b32_e32 v116, v0
	v_mov_b32_e32 v117, v0
	v_mov_b32_e32 v118, v0
	v_mov_b32_e32 v119, v0
	v_mov_b32_e32 v72, v0
	v_mov_b32_e32 v73, v0
	v_mov_b32_e32 v74, v0
	v_mov_b32_e32 v75, v0
	v_mov_b32_e32 v76, v0
	v_mov_b32_e32 v77, v0
	v_mov_b32_e32 v78, v0
	v_mov_b32_e32 v79, v0
	v_mov_b32_e32 v88, v0
	v_mov_b32_e32 v89, v0
	v_mov_b32_e32 v90, v0
	v_mov_b32_e32 v91, v0
	v_mov_b32_e32 v92, v0
	v_mov_b32_e32 v93, v0
	v_mov_b32_e32 v94, v0
	v_mov_b32_e32 v95, v0
	v_mov_b32_e32 v104, v0
	v_mov_b32_e32 v105, v0
	v_mov_b32_e32 v106, v0
	v_mov_b32_e32 v107, v0
	v_mov_b32_e32 v108, v0
	v_mov_b32_e32 v109, v0
	v_mov_b32_e32 v110, v0
	v_mov_b32_e32 v111, v0
	v_mov_b32_e32 v120, v0
	v_mov_b32_e32 v121, v0
	v_mov_b32_e32 v122, v0
	v_mov_b32_e32 v123, v0
	v_mov_b32_e32 v124, v0
	v_mov_b32_e32 v125, v0
	v_mov_b32_e32 v126, v0
	v_mov_b32_e32 v127, v0
